# final normalisation: the 512 sample rows spread over every fourth wave of the grid instead of workgroups 0..63 (tail balancing)
# baseline (speedup 1.0000x reference)
; __device__ __forceinline__ void final_phase(const Params& p) {
;   const float* part = (const float*)(p.ws + O_PART);
;   const float* g = p.in[40];
;   const int lane = threadIdx.x & 63, wave = threadIdx.x >> 6;
;   for (int row = blockIdx.x * 8 + wave; row < MT; row += gridDim.x * 8) {
;     float s = (lane < 16) ? part[(size_t)row * 16 + lane] : 0.f;
;     s = wsum64(s);
;     const float rs = rsqrtf(s * (1.0f / 1024.0f) + 1e-6f);
;     float* xr = p.out + (size_t)row * 1024;
; #pragma unroll
;     for (int i = 0; i < 4; i++) {
;       float4 v = *(float4*)(xr + i * 256 + lane * 4);
.LBB0_2340:
	v_lshrrev_b32_e32 v42, 6, v128
	v_and_b32_e32 v43, 63, v128
	v_readlane_b32 s1, v254, 0
	v_readfirstlane_b32 s0, v42
	v_lshlrev_b32_e32 v40, 4, v43
	v_and_b32_e32 v44, 15, v43
	v_lshlrev_b32_e32 v41, 2, v44
	v_cmp_gt_u32_e32 vcc, 16, v43
	s_lshl_b32 s1, s1, 3
	s_add_u32 s2, s1, s0
	s_add_u32 s16, s2, 8192
	s_lshr_b32 s17, s2, 2
	s_add_u32 s17, s17, 16384
	s_and_b32 s18, s2, 3
	s_cmp_eq_u32 s18, 0
	s_cselect_b32 s18, 9, 8
	s_mov_b32 s3, 0
	s_lshl_b32 s12, s42, 3
	s_add_u32 s96, s96, 0x2e00100
	s_addc_u32 s97, s97, 0
	global_load_dwordx4 v[16:19], v40, s[92:93]
	global_load_dwordx4 v[20:23], v40, s[92:93] offset:1024
	global_load_dwordx4 v[24:27], v40, s[92:93] offset:2048
	global_load_dwordx4 v[28:31], v40, s[92:93] offset:3072
	s_mov_b32 s14, s2
	s_lshl_b32 s4, s2, 12
	s_add_u32 s8, s94, s4
	s_addc_u32 s9, s95, 0
	s_lshl_b32 s4, s2, 6
	s_add_u32 s6, s96, s4
	s_addc_u32 s7, s97, 0
	global_load_dwordx4 v[0:3], v40, s[8:9]
	global_load_dwordx4 v[4:7], v40, s[8:9] offset:1024
	global_load_dwordx4 v[8:11], v40, s[8:9] offset:2048
	global_load_dwordx4 v[12:15], v40, s[8:9] offset:3072
	global_load_dword v32, v41, s[6:7]
	s_add_u32 s3, s3, 1
	s_add_u32 s2, s2, 2048
	s_cmp_eq_u32 s3, 4
	s_cselect_b32 s2, s16, s2
	s_cmp_eq_u32 s3, 8
	s_cselect_b32 s2, s17, s2
	s_cmp_ge_u32 s3, s18
	s_mov_b32 s15, s2
	s_lshl_b32 s4, s2, 12
	s_add_u32 s10, s94, s4
	s_addc_u32 s11, s95, 0
	s_lshl_b32 s4, s2, 6
	s_add_u32 s6, s96, s4
	s_addc_u32 s7, s97, 0
	global_load_dwordx4 v[48:51], v40, s[10:11]
	global_load_dwordx4 v[52:55], v40, s[10:11] offset:1024
	global_load_dwordx4 v[56:59], v40, s[10:11] offset:2048
	global_load_dwordx4 v[60:63], v40, s[10:11] offset:3072
	global_load_dword v80, v41, s[6:7]
	s_waitcnt vmcnt(5)
	s_cmp_lt_u32 s14, 16384
	s_cbranch_scc1 .Lfin_prompt_f
	v_mul_f32_e32 v42, v0, v0
	v_fmac_f32_e32 v42, v1, v1
	v_fmac_f32_e32 v42, v2, v2
	v_fmac_f32_e32 v42, v3, v3
	v_fmac_f32_e32 v42, v4, v4
	v_fmac_f32_e32 v42, v5, v5
	v_fmac_f32_e32 v42, v6, v6
	v_fmac_f32_e32 v42, v7, v7
	v_fmac_f32_e32 v42, v8, v8
	v_fmac_f32_e32 v42, v9, v9
	v_fmac_f32_e32 v42, v10, v10
	v_fmac_f32_e32 v42, v11, v11
	v_fmac_f32_e32 v42, v12, v12
	v_fmac_f32_e32 v42, v13, v13
	v_fmac_f32_e32 v42, v14, v14
	v_fmac_f32_e32 v42, v15, v15
	s_branch .Lfin_sum_f

; __device__ __forceinline__ void final_phase(const Params& p) {
;     ...
;   for (int row = blockIdx.x * 8 + wave; row < MT; row += gridDim.x * 8) {
;     float s = (lane < 16) ? part[(size_t)row * 16 + lane] : 0.f;
;     s = wsum64(s);
;     const float rs = rsqrtf(s * (1.0f / 1024.0f) + 1e-6f);
;     float* xr = p.out + (size_t)row * 1024;
; #pragma unroll
;     for (int i = 0; i < 4; i++) {
;       float4 v = *(float4*)(xr + i * 256 + lane * 4);
.Lfin_loop:
	s_mov_b32 s13, 0
	s_add_u32 s3, s3, 1
	s_add_u32 s2, s2, 2048
	s_cmp_eq_u32 s3, 4
	s_cselect_b32 s2, s16, s2
	s_cmp_eq_u32 s3, 8
	s_cselect_b32 s2, s17, s2
	s_cmp_ge_u32 s3, s18
	s_cbranch_scc1 .Lfin_nomore_a
	s_mov_b32 s14, s2
	s_lshl_b32 s4, s2, 12
	s_add_u32 s8, s94, s4
	s_addc_u32 s9, s95, 0
	s_lshl_b32 s4, s2, 6
	s_add_u32 s6, s96, s4
	s_addc_u32 s7, s97, 0
	global_load_dwordx4 v[0:3], v40, s[8:9]
	global_load_dwordx4 v[4:7], v40, s[8:9] offset:1024
	global_load_dwordx4 v[8:11], v40, s[8:9] offset:2048
	global_load_dwordx4 v[12:15], v40, s[8:9] offset:3072
	global_load_dword v32, v41, s[6:7]
	s_waitcnt vmcnt(9)
	s_branch .Lfin_go_a

; __device__ __forceinline__ void final_phase(const Params& p) {
;     ...
;     float s = (lane < 16) ? part[(size_t)row * 16 + lane] : 0.f;
;     s = wsum64(s);
;     const float rs = rsqrtf(s * (1.0f / 1024.0f) + 1e-6f);
;     float* xr = p.out + (size_t)row * 1024;
; #pragma unroll
;     for (int i = 0; i < 4; i++) {
;       float4 v = *(float4*)(xr + i * 256 + lane * 4);
;       float4 gg = *(const float4*)(g + i * 256 + lane * 4);
;       v.x *= rs * gg.x; v.y *= rs * gg.y; v.z *= rs * gg.z; v.w *= rs * gg.w;
;       *(float4*)(xr + i * 256 + lane * 4) = v;
;     }
.Lfin_sum_a:
	s_nop 1
	v_add_f32_dpp v42, v42, v42 quad_perm:[1,0,3,2] row_mask:0xf bank_mask:0xf
	s_nop 1
	v_add_f32_dpp v42, v42, v42 quad_perm:[2,3,0,1] row_mask:0xf bank_mask:0xf
	s_nop 1
	v_add_f32_dpp v42, v42, v42 row_half_mirror row_mask:0xf bank_mask:0xf
	s_nop 1
	v_add_f32_dpp v42, v42, v42 row_mirror row_mask:0xf bank_mask:0xf
	v_mov_b32_e32 v43, v42
	s_nop 1
	v_permlane16_swap_b32_e32 v43, v42
	v_add_f32_e32 v42, v42, v43
	v_mov_b32_e32 v43, v42
	s_nop 1
	v_permlane32_swap_b32_e32 v43, v42
	v_add_f32_e32 v42, v42, v43
	v_mov_b32_e32 v43, 0x358637bd
	v_fmamk_f32 v42, v42, 0x3a800000, v43
	v_rsq_f32_e32 v42, v42
	s_nop 0
	v_mul_f32_e32 v44, v42, v16
	v_mul_f32_e32 v48, v48, v44
	v_mul_f32_e32 v45, v42, v17
	v_mul_f32_e32 v49, v49, v45
	v_mul_f32_e32 v46, v42, v18
	v_mul_f32_e32 v50, v50, v46
	v_mul_f32_e32 v47, v42, v19
	v_mul_f32_e32 v51, v51, v47
	v_mul_f32_e32 v44, v42, v20
	v_mul_f32_e32 v52, v52, v44
	v_mul_f32_e32 v45, v42, v21
	v_mul_f32_e32 v53, v53, v45
	v_mul_f32_e32 v46, v42, v22
	v_mul_f32_e32 v54, v54, v46
	v_mul_f32_e32 v47, v42, v23
	v_mul_f32_e32 v55, v55, v47
	v_mul_f32_e32 v44, v42, v24
	v_mul_f32_e32 v56, v56, v44
	v_mul_f32_e32 v45, v42, v25
	v_mul_f32_e32 v57, v57, v45
	v_mul_f32_e32 v46, v42, v26
	v_mul_f32_e32 v58, v58, v46
	v_mul_f32_e32 v47, v42, v27
	v_mul_f32_e32 v59, v59, v47
	v_mul_f32_e32 v44, v42, v28
	v_mul_f32_e32 v60, v60, v44
	v_mul_f32_e32 v45, v42, v29
	v_mul_f32_e32 v61, v61, v45
	v_mul_f32_e32 v46, v42, v30
	v_mul_f32_e32 v62, v62, v46
	v_mul_f32_e32 v47, v42, v31
	v_mul_f32_e32 v63, v63, v47
	global_store_dwordx4 v40, v[48:51], s[10:11]
	global_store_dwordx4 v40, v[52:55], s[10:11] offset:1024
	global_store_dwordx4 v40, v[56:59], s[10:11] offset:2048
	global_store_dwordx4 v40, v[60:63], s[10:11] offset:3072
	s_cmp_eq_u32 s13, 1
	s_cbranch_scc1 .Lfin_done
	s_mov_b32 s13, 0
	s_add_u32 s3, s3, 1
	s_add_u32 s2, s2, 2048
	s_cmp_eq_u32 s3, 4
	s_cselect_b32 s2, s16, s2
	s_cmp_eq_u32 s3, 8
	s_cselect_b32 s2, s17, s2
	s_cmp_ge_u32 s3, s18
	s_cbranch_scc1 .Lfin_nomore_b
	s_mov_b32 s15, s2
	s_lshl_b32 s4, s2, 12
	s_add_u32 s10, s94, s4
	s_addc_u32 s11, s95, 0
	s_lshl_b32 s4, s2, 6
	s_add_u32 s6, s96, s4
	s_addc_u32 s7, s97, 0
	global_load_dwordx4 v[48:51], v40, s[10:11]
	global_load_dwordx4 v[52:55], v40, s[10:11] offset:1024
	global_load_dwordx4 v[56:59], v40, s[10:11] offset:2048
	global_load_dwordx4 v[60:63], v40, s[10:11] offset:3072
	global_load_dword v80, v41, s[6:7]
	s_waitcnt vmcnt(9)
	s_branch .Lfin_go_b
